# SSD state pass with batched loads two batches ahead (carry-free 64-bit pointer steps), on top of previous best
# speedup vs baseline: 1.0065x; 1.0065x over previous
.LBB0_729:
	v_lshlrev_b32_e32 v2, 1, v8
	v_ashrrev_i32_e32 v6, 15, v8
	v_and_b32_e32 v4, 0xc000, v2
	v_and_b32_e32 v2, 0x1fff, v9
	v_lshlrev_b32_e32 v3, 2, v8
	v_ashrrev_i32_e32 v7, 31, v6
	v_lshlrev_b32_e32 v5, 1, v2
	v_and_b32_e32 v12, 0x18000, v3
	v_lshlrev_b32_e32 v13, 2, v2
	v_lshlrev_b64 v[2:3], 22, v[6:7]
	v_lshrrev_b32_e32 v10, 11, v8
	v_or3_b32 v2, v2, v4, v5
	v_lshlrev_b64 v[4:5], 10, v[6:7]
	v_lshlrev_b64 v[6:7], 23, v[6:7]
	v_and_or_b32 v4, v10, 12, v4
	v_or3_b32 v6, v6, v12, v13
	v_mov_b32_e32 v12, 0
	s_mov_b32 s2, -8
	s_waitcnt lgkmcnt(0)
	v_mov_b32_e32 v82, 0x20000
	v_mov_b32_e32 v83, 0
	v_mov_b32_e32 v84, 0x10000
	v_mov_b32_e32 v85, 0
	v_lshl_add_u64 v[74:75], s[8:9], 0, v[6:7]
	v_add_co_u32_e32 v74, vcc, 0x16100000, v74
	s_nop 1
	v_addc_co_u32_e32 v75, vcc, 0, v75, vcc
	v_lshl_add_u64 v[76:77], s[8:9], 0, v[4:5]
	v_add_co_u32_e32 v76, vcc, 0xc0000, v76
	s_nop 1
	v_addc_co_u32_e32 v77, vcc, 0, v77, vcc
	v_lshl_add_u64 v[78:79], s[8:9], 0, v[2:3]
	v_add_co_u32_e32 v78, vcc, 0x17100000, v78
	s_nop 1
	v_addc_co_u32_e32 v79, vcc, 0, v79, vcc
	global_load_dword v26, v[74:75], off
	v_lshl_add_u64 v[74:75], v[74:75], 0, v[82:83]
	global_load_dword v50, v[76:77], off
	global_load_dword v27, v[74:75], off
	v_lshl_add_u64 v[74:75], v[74:75], 0, v[82:83]
	global_load_dword v51, v[76:77], off offset:16
	global_load_dword v28, v[74:75], off
	v_lshl_add_u64 v[74:75], v[74:75], 0, v[82:83]
	global_load_dword v52, v[76:77], off offset:32
	global_load_dword v29, v[74:75], off
	v_lshl_add_u64 v[74:75], v[74:75], 0, v[82:83]
	global_load_dword v53, v[76:77], off offset:48
	global_load_dword v30, v[74:75], off
	v_lshl_add_u64 v[74:75], v[74:75], 0, v[82:83]
	global_load_dword v54, v[76:77], off offset:64
	global_load_dword v31, v[74:75], off
	v_lshl_add_u64 v[74:75], v[74:75], 0, v[82:83]
	global_load_dword v55, v[76:77], off offset:80
	global_load_dword v32, v[74:75], off
	v_lshl_add_u64 v[74:75], v[74:75], 0, v[82:83]
	global_load_dword v56, v[76:77], off offset:96
	global_load_dword v33, v[74:75], off
	v_lshl_add_u64 v[74:75], v[74:75], 0, v[82:83]
	global_load_dword v57, v[76:77], off offset:112
	global_load_dword v34, v[74:75], off
	v_lshl_add_u64 v[74:75], v[74:75], 0, v[82:83]
	global_load_dword v58, v[76:77], off offset:128
	global_load_dword v35, v[74:75], off
	v_lshl_add_u64 v[74:75], v[74:75], 0, v[82:83]
	global_load_dword v59, v[76:77], off offset:144
	global_load_dword v36, v[74:75], off
	v_lshl_add_u64 v[74:75], v[74:75], 0, v[82:83]
	global_load_dword v60, v[76:77], off offset:160
	global_load_dword v37, v[74:75], off
	v_lshl_add_u64 v[74:75], v[74:75], 0, v[82:83]
	global_load_dword v61, v[76:77], off offset:176
	global_load_dword v38, v[74:75], off
	v_lshl_add_u64 v[74:75], v[74:75], 0, v[82:83]
	global_load_dword v62, v[76:77], off offset:192
	global_load_dword v39, v[74:75], off
	v_lshl_add_u64 v[74:75], v[74:75], 0, v[82:83]
	global_load_dword v63, v[76:77], off offset:208
	global_load_dword v40, v[74:75], off
	v_lshl_add_u64 v[74:75], v[74:75], 0, v[82:83]
	global_load_dword v64, v[76:77], off offset:224
	global_load_dword v41, v[74:75], off
	v_lshl_add_u64 v[74:75], v[74:75], 0, v[82:83]
	global_load_dword v65, v[76:77], off offset:240
	global_load_dword v42, v[74:75], off
	v_lshl_add_u64 v[74:75], v[74:75], 0, v[82:83]
	global_load_dword v66, v[76:77], off offset:256
	global_load_dword v43, v[74:75], off
	v_lshl_add_u64 v[74:75], v[74:75], 0, v[82:83]
	global_load_dword v67, v[76:77], off offset:272
	global_load_dword v44, v[74:75], off
	v_lshl_add_u64 v[74:75], v[74:75], 0, v[82:83]
	global_load_dword v68, v[76:77], off offset:288
	global_load_dword v45, v[74:75], off
	v_lshl_add_u64 v[74:75], v[74:75], 0, v[82:83]
	global_load_dword v69, v[76:77], off offset:304
	global_load_dword v46, v[74:75], off
	v_lshl_add_u64 v[74:75], v[74:75], 0, v[82:83]
	global_load_dword v70, v[76:77], off offset:320
	global_load_dword v47, v[74:75], off
	v_lshl_add_u64 v[74:75], v[74:75], 0, v[82:83]
	global_load_dword v71, v[76:77], off offset:336
	global_load_dword v48, v[74:75], off
	v_lshl_add_u64 v[74:75], v[74:75], 0, v[82:83]
	global_load_dword v72, v[76:77], off offset:352
	global_load_dword v49, v[74:75], off
	v_lshl_add_u64 v[74:75], v[74:75], 0, v[82:83]
	global_load_dword v73, v[76:77], off offset:368
	s_waitcnt vmcnt(32)
	v_cvt_pk_bf16_f32 v80, v12, v11
	v_mul_f32_e32 v81, 0x3fb8aa3b, v50
	global_store_short v[78:79], v80, off
	v_exp_f32_e32 v81, v81
	v_lshl_add_u64 v[78:79], v[78:79], 0, v[84:85]
	v_fmac_f32_e32 v26, v12, v81
	v_cvt_pk_bf16_f32 v80, v26, v11
	v_mul_f32_e32 v81, 0x3fb8aa3b, v51
	global_store_short v[78:79], v80, off
	v_exp_f32_e32 v81, v81
	v_lshl_add_u64 v[78:79], v[78:79], 0, v[84:85]
	v_fmac_f32_e32 v27, v26, v81
	v_cvt_pk_bf16_f32 v80, v27, v11
	v_mul_f32_e32 v81, 0x3fb8aa3b, v52
	global_store_short v[78:79], v80, off
	v_exp_f32_e32 v81, v81
	v_lshl_add_u64 v[78:79], v[78:79], 0, v[84:85]
	v_fmac_f32_e32 v28, v27, v81
	v_cvt_pk_bf16_f32 v80, v28, v11
	v_mul_f32_e32 v81, 0x3fb8aa3b, v53
	global_store_short v[78:79], v80, off
	v_exp_f32_e32 v81, v81
	v_lshl_add_u64 v[78:79], v[78:79], 0, v[84:85]
	v_fmac_f32_e32 v29, v28, v81
	v_cvt_pk_bf16_f32 v80, v29, v11
	v_mul_f32_e32 v81, 0x3fb8aa3b, v54
	global_store_short v[78:79], v80, off
	v_exp_f32_e32 v81, v81
	v_lshl_add_u64 v[78:79], v[78:79], 0, v[84:85]
	v_fmac_f32_e32 v30, v29, v81
	v_cvt_pk_bf16_f32 v80, v30, v11
	v_mul_f32_e32 v81, 0x3fb8aa3b, v55
	global_store_short v[78:79], v80, off
	v_exp_f32_e32 v81, v81
	v_lshl_add_u64 v[78:79], v[78:79], 0, v[84:85]
	v_fmac_f32_e32 v31, v30, v81
	v_cvt_pk_bf16_f32 v80, v31, v11
	v_mul_f32_e32 v81, 0x3fb8aa3b, v56
	global_store_short v[78:79], v80, off
	v_exp_f32_e32 v81, v81
	v_lshl_add_u64 v[78:79], v[78:79], 0, v[84:85]
	v_fmac_f32_e32 v32, v31, v81
	v_cvt_pk_bf16_f32 v80, v32, v11
	v_mul_f32_e32 v81, 0x3fb8aa3b, v57
	global_store_short v[78:79], v80, off
	v_exp_f32_e32 v81, v81
	v_lshl_add_u64 v[78:79], v[78:79], 0, v[84:85]
	v_fmac_f32_e32 v33, v32, v81
	global_load_dword v26, v[74:75], off
	v_lshl_add_u64 v[74:75], v[74:75], 0, v[82:83]
	global_load_dword v50, v[76:77], off offset:384
	global_load_dword v27, v[74:75], off
	v_lshl_add_u64 v[74:75], v[74:75], 0, v[82:83]
	global_load_dword v51, v[76:77], off offset:400
	global_load_dword v28, v[74:75], off
	v_lshl_add_u64 v[74:75], v[74:75], 0, v[82:83]
	global_load_dword v52, v[76:77], off offset:416
	global_load_dword v29, v[74:75], off
	v_lshl_add_u64 v[74:75], v[74:75], 0, v[82:83]
	global_load_dword v53, v[76:77], off offset:432
	global_load_dword v30, v[74:75], off
	v_lshl_add_u64 v[74:75], v[74:75], 0, v[82:83]
	global_load_dword v54, v[76:77], off offset:448
	global_load_dword v31, v[74:75], off
	v_lshl_add_u64 v[74:75], v[74:75], 0, v[82:83]
	global_load_dword v55, v[76:77], off offset:464
	global_load_dword v32, v[74:75], off
	v_lshl_add_u64 v[74:75], v[74:75], 0, v[82:83]
	global_load_dword v56, v[76:77], off offset:480
	global_load_dword v33, v[74:75], off
	v_lshl_add_u64 v[74:75], v[74:75], 0, v[82:83]
	global_load_dword v57, v[76:77], off offset:496
	s_waitcnt vmcnt(40)
	v_cvt_pk_bf16_f32 v80, v33, v11
	v_mul_f32_e32 v81, 0x3fb8aa3b, v58
	global_store_short v[78:79], v80, off
	v_exp_f32_e32 v81, v81
	v_lshl_add_u64 v[78:79], v[78:79], 0, v[84:85]
	v_fmac_f32_e32 v34, v33, v81
	v_cvt_pk_bf16_f32 v80, v34, v11
	v_mul_f32_e32 v81, 0x3fb8aa3b, v59
	global_store_short v[78:79], v80, off
	v_exp_f32_e32 v81, v81
	v_lshl_add_u64 v[78:79], v[78:79], 0, v[84:85]
	v_fmac_f32_e32 v35, v34, v81
	v_cvt_pk_bf16_f32 v80, v35, v11
	v_mul_f32_e32 v81, 0x3fb8aa3b, v60
	global_store_short v[78:79], v80, off
	v_exp_f32_e32 v81, v81
	v_lshl_add_u64 v[78:79], v[78:79], 0, v[84:85]
	v_fmac_f32_e32 v36, v35, v81
	v_cvt_pk_bf16_f32 v80, v36, v11
	v_mul_f32_e32 v81, 0x3fb8aa3b, v61
	global_store_short v[78:79], v80, off
	v_exp_f32_e32 v81, v81
	v_lshl_add_u64 v[78:79], v[78:79], 0, v[84:85]
	v_fmac_f32_e32 v37, v36, v81
	v_cvt_pk_bf16_f32 v80, v37, v11
	v_mul_f32_e32 v81, 0x3fb8aa3b, v62
	global_store_short v[78:79], v80, off
	v_exp_f32_e32 v81, v81
	v_lshl_add_u64 v[78:79], v[78:79], 0, v[84:85]
	v_fmac_f32_e32 v38, v37, v81
	v_cvt_pk_bf16_f32 v80, v38, v11
	v_mul_f32_e32 v81, 0x3fb8aa3b, v63
	global_store_short v[78:79], v80, off
	v_exp_f32_e32 v81, v81
	v_lshl_add_u64 v[78:79], v[78:79], 0, v[84:85]
	v_fmac_f32_e32 v39, v38, v81
	v_cvt_pk_bf16_f32 v80, v39, v11
	v_mul_f32_e32 v81, 0x3fb8aa3b, v64
	global_store_short v[78:79], v80, off
	v_exp_f32_e32 v81, v81
	v_lshl_add_u64 v[78:79], v[78:79], 0, v[84:85]
	v_fmac_f32_e32 v40, v39, v81
	v_cvt_pk_bf16_f32 v80, v40, v11
	v_mul_f32_e32 v81, 0x3fb8aa3b, v65
	global_store_short v[78:79], v80, off
	v_exp_f32_e32 v81, v81
	v_lshl_add_u64 v[78:79], v[78:79], 0, v[84:85]
	v_fmac_f32_e32 v41, v40, v81
	global_load_dword v34, v[74:75], off
	v_lshl_add_u64 v[74:75], v[74:75], 0, v[82:83]
	global_load_dword v58, v[76:77], off offset:512
	global_load_dword v35, v[74:75], off
	v_lshl_add_u64 v[74:75], v[74:75], 0, v[82:83]
	global_load_dword v59, v[76:77], off offset:528
	global_load_dword v36, v[74:75], off
	v_lshl_add_u64 v[74:75], v[74:75], 0, v[82:83]
	global_load_dword v60, v[76:77], off offset:544
	global_load_dword v37, v[74:75], off
	v_lshl_add_u64 v[74:75], v[74:75], 0, v[82:83]
	global_load_dword v61, v[76:77], off offset:560
	global_load_dword v38, v[74:75], off
	v_lshl_add_u64 v[74:75], v[74:75], 0, v[82:83]
	global_load_dword v62, v[76:77], off offset:576
	global_load_dword v39, v[74:75], off
	v_lshl_add_u64 v[74:75], v[74:75], 0, v[82:83]
	global_load_dword v63, v[76:77], off offset:592
	global_load_dword v40, v[74:75], off
	v_lshl_add_u64 v[74:75], v[74:75], 0, v[82:83]
	global_load_dword v64, v[76:77], off offset:608
	global_load_dword v41, v[74:75], off
	v_lshl_add_u64 v[74:75], v[74:75], 0, v[82:83]
	global_load_dword v65, v[76:77], off offset:624
	s_waitcnt vmcnt(40)
	v_cvt_pk_bf16_f32 v80, v41, v11
	v_mul_f32_e32 v81, 0x3fb8aa3b, v66
	global_store_short v[78:79], v80, off
	v_exp_f32_e32 v81, v81
	v_lshl_add_u64 v[78:79], v[78:79], 0, v[84:85]
	v_fmac_f32_e32 v42, v41, v81
	v_cvt_pk_bf16_f32 v80, v42, v11
	v_mul_f32_e32 v81, 0x3fb8aa3b, v67
	global_store_short v[78:79], v80, off
	v_exp_f32_e32 v81, v81
	v_lshl_add_u64 v[78:79], v[78:79], 0, v[84:85]
	v_fmac_f32_e32 v43, v42, v81
	v_cvt_pk_bf16_f32 v80, v43, v11
	v_mul_f32_e32 v81, 0x3fb8aa3b, v68
	global_store_short v[78:79], v80, off
	v_exp_f32_e32 v81, v81
	v_lshl_add_u64 v[78:79], v[78:79], 0, v[84:85]
	v_fmac_f32_e32 v44, v43, v81
	v_cvt_pk_bf16_f32 v80, v44, v11
	v_mul_f32_e32 v81, 0x3fb8aa3b, v69
	global_store_short v[78:79], v80, off
	v_exp_f32_e32 v81, v81
	v_lshl_add_u64 v[78:79], v[78:79], 0, v[84:85]
	v_fmac_f32_e32 v45, v44, v81
	v_cvt_pk_bf16_f32 v80, v45, v11
	v_mul_f32_e32 v81, 0x3fb8aa3b, v70
	global_store_short v[78:79], v80, off
	v_exp_f32_e32 v81, v81
	v_lshl_add_u64 v[78:79], v[78:79], 0, v[84:85]
	v_fmac_f32_e32 v46, v45, v81
	v_cvt_pk_bf16_f32 v80, v46, v11
	v_mul_f32_e32 v81, 0x3fb8aa3b, v71
	global_store_short v[78:79], v80, off
	v_exp_f32_e32 v81, v81
	v_lshl_add_u64 v[78:79], v[78:79], 0, v[84:85]
	v_fmac_f32_e32 v47, v46, v81
	v_cvt_pk_bf16_f32 v80, v47, v11
	v_mul_f32_e32 v81, 0x3fb8aa3b, v72
	global_store_short v[78:79], v80, off
	v_exp_f32_e32 v81, v81
	v_lshl_add_u64 v[78:79], v[78:79], 0, v[84:85]
	v_fmac_f32_e32 v48, v47, v81
	v_cvt_pk_bf16_f32 v80, v48, v11
	v_mul_f32_e32 v81, 0x3fb8aa3b, v73
	global_store_short v[78:79], v80, off
	v_exp_f32_e32 v81, v81
	v_lshl_add_u64 v[78:79], v[78:79], 0, v[84:85]
	v_fmac_f32_e32 v49, v48, v81
	global_load_dword v42, v[74:75], off
	v_lshl_add_u64 v[74:75], v[74:75], 0, v[82:83]
	global_load_dword v66, v[76:77], off offset:640
	global_load_dword v43, v[74:75], off
	v_lshl_add_u64 v[74:75], v[74:75], 0, v[82:83]
	global_load_dword v67, v[76:77], off offset:656
	global_load_dword v44, v[74:75], off
	v_lshl_add_u64 v[74:75], v[74:75], 0, v[82:83]
	global_load_dword v68, v[76:77], off offset:672
	global_load_dword v45, v[74:75], off
	v_lshl_add_u64 v[74:75], v[74:75], 0, v[82:83]
	global_load_dword v69, v[76:77], off offset:688
	global_load_dword v46, v[74:75], off
	v_lshl_add_u64 v[74:75], v[74:75], 0, v[82:83]
	global_load_dword v70, v[76:77], off offset:704
	global_load_dword v47, v[74:75], off
	v_lshl_add_u64 v[74:75], v[74:75], 0, v[82:83]
	global_load_dword v71, v[76:77], off offset:720
	global_load_dword v48, v[74:75], off
	v_lshl_add_u64 v[74:75], v[74:75], 0, v[82:83]
	global_load_dword v72, v[76:77], off offset:736
	global_load_dword v49, v[74:75], off
	v_lshl_add_u64 v[74:75], v[74:75], 0, v[82:83]
	global_load_dword v73, v[76:77], off offset:752
	s_waitcnt vmcnt(40)
	v_cvt_pk_bf16_f32 v80, v49, v11
	v_mul_f32_e32 v81, 0x3fb8aa3b, v50
	global_store_short v[78:79], v80, off
	v_exp_f32_e32 v81, v81
	v_lshl_add_u64 v[78:79], v[78:79], 0, v[84:85]
	v_fmac_f32_e32 v26, v49, v81
	v_cvt_pk_bf16_f32 v80, v26, v11
	v_mul_f32_e32 v81, 0x3fb8aa3b, v51
	global_store_short v[78:79], v80, off
	v_exp_f32_e32 v81, v81
	v_lshl_add_u64 v[78:79], v[78:79], 0, v[84:85]
	v_fmac_f32_e32 v27, v26, v81
	v_cvt_pk_bf16_f32 v80, v27, v11
	v_mul_f32_e32 v81, 0x3fb8aa3b, v52
	global_store_short v[78:79], v80, off
	v_exp_f32_e32 v81, v81
	v_lshl_add_u64 v[78:79], v[78:79], 0, v[84:85]
	v_fmac_f32_e32 v28, v27, v81
	v_cvt_pk_bf16_f32 v80, v28, v11
	v_mul_f32_e32 v81, 0x3fb8aa3b, v53
	global_store_short v[78:79], v80, off
	v_exp_f32_e32 v81, v81
	v_lshl_add_u64 v[78:79], v[78:79], 0, v[84:85]
	v_fmac_f32_e32 v29, v28, v81
	v_cvt_pk_bf16_f32 v80, v29, v11
	v_mul_f32_e32 v81, 0x3fb8aa3b, v54
	global_store_short v[78:79], v80, off
	v_exp_f32_e32 v81, v81
	v_lshl_add_u64 v[78:79], v[78:79], 0, v[84:85]
	v_fmac_f32_e32 v30, v29, v81
	v_cvt_pk_bf16_f32 v80, v30, v11
	v_mul_f32_e32 v81, 0x3fb8aa3b, v55
	global_store_short v[78:79], v80, off
	v_exp_f32_e32 v81, v81
	v_lshl_add_u64 v[78:79], v[78:79], 0, v[84:85]
	v_fmac_f32_e32 v31, v30, v81
	v_cvt_pk_bf16_f32 v80, v31, v11
	v_mul_f32_e32 v81, 0x3fb8aa3b, v56
	global_store_short v[78:79], v80, off
	v_exp_f32_e32 v81, v81
	v_lshl_add_u64 v[78:79], v[78:79], 0, v[84:85]
	v_fmac_f32_e32 v32, v31, v81
	v_cvt_pk_bf16_f32 v80, v32, v11
	v_mul_f32_e32 v81, 0x3fb8aa3b, v57
	global_store_short v[78:79], v80, off
	v_exp_f32_e32 v81, v81
	v_lshl_add_u64 v[78:79], v[78:79], 0, v[84:85]
	v_fmac_f32_e32 v33, v32, v81
	global_load_dword v26, v[74:75], off
	v_lshl_add_u64 v[74:75], v[74:75], 0, v[82:83]
	global_load_dword v50, v[76:77], off offset:768
	global_load_dword v27, v[74:75], off
	v_lshl_add_u64 v[74:75], v[74:75], 0, v[82:83]
	global_load_dword v51, v[76:77], off offset:784
	global_load_dword v28, v[74:75], off
	v_lshl_add_u64 v[74:75], v[74:75], 0, v[82:83]
	global_load_dword v52, v[76:77], off offset:800
	global_load_dword v29, v[74:75], off
	v_lshl_add_u64 v[74:75], v[74:75], 0, v[82:83]
	global_load_dword v53, v[76:77], off offset:816
	global_load_dword v30, v[74:75], off
	v_lshl_add_u64 v[74:75], v[74:75], 0, v[82:83]
	global_load_dword v54, v[76:77], off offset:832
	global_load_dword v31, v[74:75], off
	v_lshl_add_u64 v[74:75], v[74:75], 0, v[82:83]
	global_load_dword v55, v[76:77], off offset:848
	global_load_dword v32, v[74:75], off
	v_lshl_add_u64 v[74:75], v[74:75], 0, v[82:83]
	global_load_dword v56, v[76:77], off offset:864
	global_load_dword v33, v[74:75], off
	v_lshl_add_u64 v[74:75], v[74:75], 0, v[82:83]
	global_load_dword v57, v[76:77], off offset:880
	s_waitcnt vmcnt(40)
	v_cvt_pk_bf16_f32 v80, v33, v11
	v_mul_f32_e32 v81, 0x3fb8aa3b, v58
	global_store_short v[78:79], v80, off
	v_exp_f32_e32 v81, v81
	v_lshl_add_u64 v[78:79], v[78:79], 0, v[84:85]
	v_fmac_f32_e32 v34, v33, v81
	v_cvt_pk_bf16_f32 v80, v34, v11
	v_mul_f32_e32 v81, 0x3fb8aa3b, v59
	global_store_short v[78:79], v80, off
	v_exp_f32_e32 v81, v81
	v_lshl_add_u64 v[78:79], v[78:79], 0, v[84:85]
	v_fmac_f32_e32 v35, v34, v81
	v_cvt_pk_bf16_f32 v80, v35, v11
	v_mul_f32_e32 v81, 0x3fb8aa3b, v60
	global_store_short v[78:79], v80, off
	v_exp_f32_e32 v81, v81
	v_lshl_add_u64 v[78:79], v[78:79], 0, v[84:85]
	v_fmac_f32_e32 v36, v35, v81
	v_cvt_pk_bf16_f32 v80, v36, v11
	v_mul_f32_e32 v81, 0x3fb8aa3b, v61
	global_store_short v[78:79], v80, off
	v_exp_f32_e32 v81, v81
	v_lshl_add_u64 v[78:79], v[78:79], 0, v[84:85]
	v_fmac_f32_e32 v37, v36, v81
	v_cvt_pk_bf16_f32 v80, v37, v11
	v_mul_f32_e32 v81, 0x3fb8aa3b, v62
	global_store_short v[78:79], v80, off
	v_exp_f32_e32 v81, v81
	v_lshl_add_u64 v[78:79], v[78:79], 0, v[84:85]
	v_fmac_f32_e32 v38, v37, v81
	v_cvt_pk_bf16_f32 v80, v38, v11
	v_mul_f32_e32 v81, 0x3fb8aa3b, v63
	global_store_short v[78:79], v80, off
	v_exp_f32_e32 v81, v81
	v_lshl_add_u64 v[78:79], v[78:79], 0, v[84:85]
	v_fmac_f32_e32 v39, v38, v81
	v_cvt_pk_bf16_f32 v80, v39, v11
	v_mul_f32_e32 v81, 0x3fb8aa3b, v64
	global_store_short v[78:79], v80, off
	v_exp_f32_e32 v81, v81
	v_lshl_add_u64 v[78:79], v[78:79], 0, v[84:85]
	v_fmac_f32_e32 v40, v39, v81
	v_cvt_pk_bf16_f32 v80, v40, v11
	v_mul_f32_e32 v81, 0x3fb8aa3b, v65
	global_store_short v[78:79], v80, off
	v_exp_f32_e32 v81, v81
	v_lshl_add_u64 v[78:79], v[78:79], 0, v[84:85]
	v_fmac_f32_e32 v41, v40, v81
	global_load_dword v34, v[74:75], off
	v_lshl_add_u64 v[74:75], v[74:75], 0, v[82:83]
	global_load_dword v58, v[76:77], off offset:896
	global_load_dword v35, v[74:75], off
	v_lshl_add_u64 v[74:75], v[74:75], 0, v[82:83]
	global_load_dword v59, v[76:77], off offset:912
	global_load_dword v36, v[74:75], off
	v_lshl_add_u64 v[74:75], v[74:75], 0, v[82:83]
	global_load_dword v60, v[76:77], off offset:928
	global_load_dword v37, v[74:75], off
	v_lshl_add_u64 v[74:75], v[74:75], 0, v[82:83]
	global_load_dword v61, v[76:77], off offset:944
	global_load_dword v38, v[74:75], off
	v_lshl_add_u64 v[74:75], v[74:75], 0, v[82:83]
	global_load_dword v62, v[76:77], off offset:960
	global_load_dword v39, v[74:75], off
	v_lshl_add_u64 v[74:75], v[74:75], 0, v[82:83]
	global_load_dword v63, v[76:77], off offset:976
	global_load_dword v40, v[74:75], off
	v_lshl_add_u64 v[74:75], v[74:75], 0, v[82:83]
	global_load_dword v64, v[76:77], off offset:992
	global_load_dword v41, v[74:75], off
	v_lshl_add_u64 v[74:75], v[74:75], 0, v[82:83]
	global_load_dword v65, v[76:77], off offset:1008
	s_waitcnt vmcnt(40)
	v_cvt_pk_bf16_f32 v80, v41, v11
	v_mul_f32_e32 v81, 0x3fb8aa3b, v66
	global_store_short v[78:79], v80, off
	v_exp_f32_e32 v81, v81
	v_lshl_add_u64 v[78:79], v[78:79], 0, v[84:85]
	v_fmac_f32_e32 v42, v41, v81
	v_cvt_pk_bf16_f32 v80, v42, v11
	v_mul_f32_e32 v81, 0x3fb8aa3b, v67
	global_store_short v[78:79], v80, off
	v_exp_f32_e32 v81, v81
	v_lshl_add_u64 v[78:79], v[78:79], 0, v[84:85]
	v_fmac_f32_e32 v43, v42, v81
	v_cvt_pk_bf16_f32 v80, v43, v11
	v_mul_f32_e32 v81, 0x3fb8aa3b, v68
	global_store_short v[78:79], v80, off
	v_exp_f32_e32 v81, v81
	v_lshl_add_u64 v[78:79], v[78:79], 0, v[84:85]
	v_fmac_f32_e32 v44, v43, v81
	v_cvt_pk_bf16_f32 v80, v44, v11
	v_mul_f32_e32 v81, 0x3fb8aa3b, v69
	global_store_short v[78:79], v80, off
	v_exp_f32_e32 v81, v81
	v_lshl_add_u64 v[78:79], v[78:79], 0, v[84:85]
	v_fmac_f32_e32 v45, v44, v81
	v_cvt_pk_bf16_f32 v80, v45, v11
	v_mul_f32_e32 v81, 0x3fb8aa3b, v70
	global_store_short v[78:79], v80, off
	v_exp_f32_e32 v81, v81
	v_lshl_add_u64 v[78:79], v[78:79], 0, v[84:85]
	v_fmac_f32_e32 v46, v45, v81
	v_cvt_pk_bf16_f32 v80, v46, v11
	v_mul_f32_e32 v81, 0x3fb8aa3b, v71
	global_store_short v[78:79], v80, off
	v_exp_f32_e32 v81, v81
	v_lshl_add_u64 v[78:79], v[78:79], 0, v[84:85]
	v_fmac_f32_e32 v47, v46, v81
	v_cvt_pk_bf16_f32 v80, v47, v11
	v_mul_f32_e32 v81, 0x3fb8aa3b, v72
	global_store_short v[78:79], v80, off
	v_exp_f32_e32 v81, v81
	v_lshl_add_u64 v[78:79], v[78:79], 0, v[84:85]
	v_fmac_f32_e32 v48, v47, v81
	v_cvt_pk_bf16_f32 v80, v48, v11
	v_mul_f32_e32 v81, 0x3fb8aa3b, v73
	global_store_short v[78:79], v80, off
	v_exp_f32_e32 v81, v81
	v_lshl_add_u64 v[78:79], v[78:79], 0, v[84:85]
	v_fmac_f32_e32 v49, v48, v81
	s_waitcnt vmcnt(24)
	v_cvt_pk_bf16_f32 v80, v49, v11
	v_mul_f32_e32 v81, 0x3fb8aa3b, v50
	global_store_short v[78:79], v80, off
	v_exp_f32_e32 v81, v81
	v_lshl_add_u64 v[78:79], v[78:79], 0, v[84:85]
	v_fmac_f32_e32 v26, v49, v81
	v_cvt_pk_bf16_f32 v80, v26, v11
	v_mul_f32_e32 v81, 0x3fb8aa3b, v51
	global_store_short v[78:79], v80, off
	v_exp_f32_e32 v81, v81
	v_lshl_add_u64 v[78:79], v[78:79], 0, v[84:85]
	v_fmac_f32_e32 v27, v26, v81
	v_cvt_pk_bf16_f32 v80, v27, v11
	v_mul_f32_e32 v81, 0x3fb8aa3b, v52
	global_store_short v[78:79], v80, off
	v_exp_f32_e32 v81, v81
	v_lshl_add_u64 v[78:79], v[78:79], 0, v[84:85]
	v_fmac_f32_e32 v28, v27, v81
	v_cvt_pk_bf16_f32 v80, v28, v11
	v_mul_f32_e32 v81, 0x3fb8aa3b, v53
	global_store_short v[78:79], v80, off
	v_exp_f32_e32 v81, v81
	v_lshl_add_u64 v[78:79], v[78:79], 0, v[84:85]
	v_fmac_f32_e32 v29, v28, v81
	v_cvt_pk_bf16_f32 v80, v29, v11
	v_mul_f32_e32 v81, 0x3fb8aa3b, v54
	global_store_short v[78:79], v80, off
	v_exp_f32_e32 v81, v81
	v_lshl_add_u64 v[78:79], v[78:79], 0, v[84:85]
	v_fmac_f32_e32 v30, v29, v81
	v_cvt_pk_bf16_f32 v80, v30, v11
	v_mul_f32_e32 v81, 0x3fb8aa3b, v55
	global_store_short v[78:79], v80, off
	v_exp_f32_e32 v81, v81
	v_lshl_add_u64 v[78:79], v[78:79], 0, v[84:85]
	v_fmac_f32_e32 v31, v30, v81
	v_cvt_pk_bf16_f32 v80, v31, v11
	v_mul_f32_e32 v81, 0x3fb8aa3b, v56
	global_store_short v[78:79], v80, off
	v_exp_f32_e32 v81, v81
	v_lshl_add_u64 v[78:79], v[78:79], 0, v[84:85]
	v_fmac_f32_e32 v32, v31, v81
	v_cvt_pk_bf16_f32 v80, v32, v11
	v_mul_f32_e32 v81, 0x3fb8aa3b, v57
	global_store_short v[78:79], v80, off
	v_exp_f32_e32 v81, v81
	v_lshl_add_u64 v[78:79], v[78:79], 0, v[84:85]
	v_fmac_f32_e32 v33, v32, v81
	s_waitcnt vmcnt(8)
	v_cvt_pk_bf16_f32 v80, v33, v11
	v_mul_f32_e32 v81, 0x3fb8aa3b, v58
	global_store_short v[78:79], v80, off
	v_exp_f32_e32 v81, v81
	v_lshl_add_u64 v[78:79], v[78:79], 0, v[84:85]
	v_fmac_f32_e32 v34, v33, v81
	v_cvt_pk_bf16_f32 v80, v34, v11
	v_mul_f32_e32 v81, 0x3fb8aa3b, v59
	global_store_short v[78:79], v80, off
	v_exp_f32_e32 v81, v81
	v_lshl_add_u64 v[78:79], v[78:79], 0, v[84:85]
	v_fmac_f32_e32 v35, v34, v81
	v_cvt_pk_bf16_f32 v80, v35, v11
	v_mul_f32_e32 v81, 0x3fb8aa3b, v60
	global_store_short v[78:79], v80, off
	v_exp_f32_e32 v81, v81
	v_lshl_add_u64 v[78:79], v[78:79], 0, v[84:85]
	v_fmac_f32_e32 v36, v35, v81
	v_cvt_pk_bf16_f32 v80, v36, v11
	v_mul_f32_e32 v81, 0x3fb8aa3b, v61
	global_store_short v[78:79], v80, off
	v_exp_f32_e32 v81, v81
	v_lshl_add_u64 v[78:79], v[78:79], 0, v[84:85]
	v_fmac_f32_e32 v37, v36, v81
	v_cvt_pk_bf16_f32 v80, v37, v11
	v_mul_f32_e32 v81, 0x3fb8aa3b, v62
	global_store_short v[78:79], v80, off
	v_exp_f32_e32 v81, v81
	v_lshl_add_u64 v[78:79], v[78:79], 0, v[84:85]
	v_fmac_f32_e32 v38, v37, v81
	v_cvt_pk_bf16_f32 v80, v38, v11
	v_mul_f32_e32 v81, 0x3fb8aa3b, v63
	global_store_short v[78:79], v80, off
	v_exp_f32_e32 v81, v81
	v_lshl_add_u64 v[78:79], v[78:79], 0, v[84:85]
	v_fmac_f32_e32 v39, v38, v81
	v_cvt_pk_bf16_f32 v80, v39, v11
	v_mul_f32_e32 v81, 0x3fb8aa3b, v64
	global_store_short v[78:79], v80, off
	v_exp_f32_e32 v81, v81
	v_lshl_add_u64 v[78:79], v[78:79], 0, v[84:85]
	v_fmac_f32_e32 v40, v39, v81
	v_cvt_pk_bf16_f32 v80, v40, v11
	v_mul_f32_e32 v81, 0x3fb8aa3b, v65
	global_store_short v[78:79], v80, off
	v_exp_f32_e32 v81, v81
	v_lshl_add_u64 v[78:79], v[78:79], 0, v[84:85]
	v_fmac_f32_e32 v41, v40, v81
	v_mov_b32_e32 v12, v41
	v_readlane_b32 s4, v243, 17
	s_mov_b32 s2, 0xffff
	s_nop 0
	v_add_u32_e32 v8, s4, v8
	v_cmp_lt_i32_e32 vcc, s2, v8
	s_or_b64 s[10:11], vcc, s[10:11]
	v_add_u16_e32 v9, s4, v9
	s_andn2_b64 exec, exec, s[10:11]
	s_cbranch_execnz .LBB0_729
